# P0: waves 4-7 run the rmsnorm row loop first and the weight transposition second (waves 0-3 keep the original order) so each SIMD pair mixes the latency-bound and the streaming part
# baseline (speedup 1.0000x reference)
.LBB0_5:
	s_or_b64 exec, exec, s[4:5]
	s_load_dwordx16 s[56:71], s[0:1], 0x40
	v_lshrrev_b32_e32 v32, 6, v0
	s_lshl_b32 s3, s2, 3
	v_or_b32_e32 v91, s3, v32
	v_writelane_b32 v252, s3, 0
	s_movk_i32 s3, 0x1800
	v_and_b32_e32 v165, 63, v0
	s_lshl_b32 s92, s82, 3
	v_cmp_gt_i32_e32 vcc, s3, v91
	v_and_b32_e32 v1, 31, v0
	v_lshlrev_b32_e32 v205, 3, v0
	v_and_b32_e32 v185, 3, v0
	v_readfirstlane_b32 s98, v0
	s_mov_b32 s99, 0
	s_nop 2
	s_cmp_lt_u32 s98, 0x100
	s_cbranch_scc1 .Lp0_orig_order
	s_mov_b32 s99, 1
	s_branch .Lp0_x_entry
.Lp0_orig_order:
	s_and_saveexec_b64 s[6:7], vcc
	s_cbranch_execz .LBB0_52
.Lp0_w_body:
	v_lshlrev_b32_e32 v2, 5, v0
	v_and_b32_e32 v14, 0x400, v2
	v_and_b32_e32 v2, 56, v205
	v_lshrrev_b32_e32 v35, 3, v165
	v_mul_u32_u24_e32 v7, 0x84, v2
	v_lshlrev_b32_e32 v2, 1, v2
	v_mov_b32_e32 v3, 0
	v_lshl_add_u32 v6, v32, 14, 0
	v_lshl_add_u64 v[10:11], s[80:81], 0, v[2:3]
	s_mov_b64 s[4:5], 0x1388800
	v_lshlrev_b32_e32 v2, 2, v35
	v_lshrrev_b32_e32 v33, 5, v165
	v_lshl_add_u64 v[4:5], v[10:11], 0, s[4:5]
	v_add3_u32 v36, v6, v7, v2
	v_bfe_i32 v2, v0, 2, 1
	s_movk_i32 s4, 0xb00
	v_lshl_add_u32 v15, v1, 2, v6
	s_movk_i32 s8, 0x84
	v_and_or_b32 v40, v2, s4, v185
	v_or_b32_e32 v2, 2, v33
	v_mov_b32_e32 v6, 0x108
	v_mad_u32_u24 v17, v2, s8, v6
	v_mov_b32_e32 v6, 0x318
	v_mad_u32_u24 v18, v2, s8, v6
	v_mov_b32_e32 v6, 0x528
	v_lshlrev_b32_e32 v12, 5, v32
	v_mad_u32_u24 v19, v2, s8, v6
	v_mov_b32_e32 v6, 0x738
	s_mov_b64 s[4:5], 0x888800
	s_waitcnt lgkmcnt(0)
	s_cmp_lg_u64 s[70:71], 0
	v_lshl_or_b32 v20, s2, 8, v12
	v_mul_u32_u24_e32 v16, 0x84, v2
	v_mad_u32_u24 v2, v2, s8, v6
	v_lshl_add_u64 v[6:7], v[10:11], 0, s[4:5]
	s_mov_b64 s[4:5], 0x688800
	s_cselect_b64 s[10:11], -1, 0
	v_add_u32_e32 v12, 0xfffff580, v20
	v_or_b32_e32 v20, v20, v1
	s_lshl_b32 s23, s2, 14
	v_or_b32_e32 v13, v14, v1
	v_mad_u32_u24 v34, v33, s8, v15
	v_lshl_add_u64 v[8:9], v[10:11], 0, s[4:5]
	s_mov_b64 s[4:5], 0x108800
	v_lshlrev_b32_e32 v41, 3, v20
	v_lshlrev_b32_e32 v42, 11, v32
	v_or_b32_e32 v14, s23, v14
	v_lshlrev_b32_e32 v20, 5, v91
	v_lshlrev_b32_e32 v21, 1, v32
	s_mov_b32 s3, 0
	v_or_b32_e32 v37, 8, v35
	v_or_b32_e32 v38, 16, v35
	v_or_b32_e32 v39, 24, v35
	v_lshl_add_u64 v[10:11], v[10:11], 0, s[4:5]
	s_mov_b64 s[8:9], 0
	s_lshl_b32 s20, s92, 5
	s_lshl_b32 s21, s92, 8
	s_lshl_b32 s22, s92, 11
	v_add_u32_e32 v43, 0xff6c0000, v14
	v_add_u32_e32 v44, 0xfffdb000, v20
	v_or_b32_e32 v45, v1, v42
	v_lshl_or_b32 v46, s2, 4, v21
	s_lshl_b32 s24, s92, 1
	v_add_u32_e32 v47, 0xffd40000, v14
	v_add_u32_e32 v48, 0xffff5000, v20
	s_movk_i32 s25, 0x57f
	s_movk_i32 s26, 0x77f
	s_movk_i32 s27, 0x127f
	s_mov_b32 s28, 0x16000
	s_mov_b32 s29, 0x2c000
	s_mov_b32 s30, 0xb000
	s_mov_b32 s31, 0x21000
	s_mov_b32 s33, 0x37000
	s_mov_b32 s34, 0x42000
	s_mov_b32 s35, 0x4d000
	s_mov_b32 s36, 0x58000
	s_mov_b32 s37, 0x63000
	s_mov_b32 s38, 0x6e000
	s_mov_b32 s39, 0x79000
	s_mov_b32 s40, 0x84000
	s_mov_b32 s41, 0x8f000
	s_mov_b32 s42, 0x9a000
	s_mov_b32 s43, 0xa5000
	s_mov_b32 s44, 0xb0000
	s_mov_b32 s45, 0xbb000
	s_mov_b32 s46, 0xc6000
	s_mov_b32 s47, 0xd1000
	s_mov_b32 s48, 0xdc000
	s_mov_b32 s49, 0xe7000
	s_mov_b32 s50, 0xf2000
	s_mov_b32 s51, 0xfd000
	s_mov_b32 s52, 0x108000
	s_mov_b32 s53, 0x113000
	s_mov_b32 s54, 0x11e000
	s_mov_b32 s55, 0x129000
	s_mov_b32 s84, 0x134000
	v_add_u32_e32 v49, v15, v17
	v_add_u32_e32 v50, v15, v19
	s_movk_i32 s85, 0xf500
	s_mov_b32 s86, 0x2e8ba2e9
	s_movk_i32 s87, 0xa80
	s_movk_i32 s88, 0xfd80
	s_movk_i32 s89, 0x2c00
	s_movk_i32 s90, 0x17ff
	v_add_u32_e32 v51, 0x400, v34
	v_add_u32_e32 v52, 0x800, v34
	v_add_u32_e32 v53, 0xc00, v34
	v_add_u32_e32 v54, 0x1000, v34
	v_add_u32_e32 v55, 0x1400, v34
	v_add_u32_e32 v56, 0x1800, v34
	v_add_u32_e32 v57, 0x1c00, v34
	v_add_u32_e32 v58, v15, v16
	v_add_u32_e32 v59, v15, v18
	v_add_u32_e32 v60, v15, v2
	v_mov_b32_e32 v61, v91
	s_branch .LBB0_8

.LBB0_52:
	s_or_b64 exec, exec, s[6:7]
	s_cmp_eq_u32 s99, 2
	s_cbranch_scc1 .Lp0_t_entry
.Lp0_x_entry:
	s_load_dwordx16 s[4:19], s[0:1], 0x0
	s_movk_i32 s0, 0x4080
	v_lshlrev_b32_e32 v164, 2, v165
	v_mov_b32_e32 v83, 0
	v_cmp_gt_i32_e32 vcc, s0, v91
	s_waitcnt lgkmcnt(0)
	v_writelane_b32 v252, s4, 1
	v_lshlrev_b32_e32 v162, 3, v165
	v_mbcnt_lo_u32_b32 v204, -1, 0
	v_writelane_b32 v252, s5, 2
	v_writelane_b32 v252, s6, 3
	v_writelane_b32 v252, s7, 4
	v_writelane_b32 v252, s8, 5
	v_writelane_b32 v252, s9, 6
	v_writelane_b32 v252, s10, 7
	v_writelane_b32 v252, s11, 8
	v_writelane_b32 v252, s12, 9
	v_writelane_b32 v252, s13, 10
	v_writelane_b32 v252, s14, 11
	v_writelane_b32 v252, s15, 12
	v_writelane_b32 v252, s16, 13
	v_writelane_b32 v252, s17, 14
	v_writelane_b32 v252, s18, 15
	v_writelane_b32 v252, s19, 16
	s_and_saveexec_b64 s[12:13], vcc
	s_cbranch_execz .LBB0_75
	v_lshlrev_b32_e32 v82, 2, v164
	global_load_dwordx4 v[2:5], v82, s[56:57]
	global_load_dwordx4 v[6:9], v82, s[56:57] offset:1024
	global_load_dwordx4 v[10:13], v82, s[56:57] offset:2048
	global_load_dwordx4 v[14:17], v82, s[56:57] offset:3072
	s_add_u32 s8, s80, 0x1908800
	s_addc_u32 s9, s81, 0
	v_and_b32_e32 v20, 1, v0
	v_and_b32_e32 v18, 0x1f0, v205
	v_mov_b32_e32 v19, v83
	v_cmp_eq_u32_e64 s[4:5], 0, v20
	v_lshl_add_u64 v[18:19], s[8:9], 0, v[18:19]
	v_lshlrev_b32_e32 v20, 9, v20
	v_mov_b32_e32 v21, v83
	v_lshl_add_u64 v[86:87], v[18:19], 0, v[20:21]
	v_lshlrev_b32_e32 v18, 2, v32
	v_mbcnt_hi_u32_b32 v94, -1, v204
	s_add_u32 s16, s80, 0xc3000
	v_mov_b32_e32 v163, v83
	v_lshl_or_b32 v88, s2, 5, v18
	v_and_b32_e32 v18, 64, v94
	s_mov_b32 s14, 0
	v_cmp_eq_u32_e64 s[0:1], 0, v165
	v_cmp_ne_u32_e64 s[6:7], 0, v165
	s_addc_u32 s17, s81, 0
	v_lshl_add_u64 v[84:85], s[8:9], 0, v[162:163]
	s_lshl_b32 s3, s82, 5
	s_mov_b64 s[18:19], 0
	s_movk_i32 s22, 0x4044
	s_movk_i32 s23, 0x3fff
	s_movk_i32 s24, 0x403f
	v_mov_b32_e32 v92, 0x358637bd
	s_mov_b32 s25, 0xf800000
	v_mov_b32_e32 v93, 0x260
	s_mov_b32 s26, 0x800000
	s_movk_i32 s27, 0x407f
	v_add_u32_e32 v95, 64, v18
	v_xor_b32_e32 v96, 1, v94
	v_xor_b32_e32 v97, 2, v94
	v_xor_b32_e32 v98, 4, v94
	v_xor_b32_e32 v99, 8, v94
	v_xor_b32_e32 v100, 16, v94
	s_branch .LBB0_55

.LBB0_75:
	s_or_b64 exec, exec, s[12:13]
	s_cmp_eq_u32 s99, 1
	s_cbranch_scc0 .Lp0_t_entry
	s_mov_b32 s99, 2
	v_lshrrev_b32_e32 v32, 6, v0
	s_lshl_b32 s3, s2, 3
	v_or_b32_e32 v91, s3, v32
	s_movk_i32 s3, 0x1800
	v_cmp_gt_i32_e32 vcc, s3, v91
	s_and_saveexec_b64 s[6:7], vcc
	s_cbranch_execz .LBB0_52
	s_branch .Lp0_w_body
.Lp0_t_entry:
	s_lshl_b32 s0, s2, 9
	v_writelane_b32 v252, s0, 17
	v_or_b32_e32 v166, s0, v0
	s_movk_i32 s0, 0x200
	v_cmp_gt_i32_e32 vcc, s0, v166
	v_ashrrev_i32_e32 v167, 31, v166
	s_and_saveexec_b64 s[0:1], vcc
	s_cbranch_execz .LBB0_77
	s_waitcnt vmcnt(3)
	v_lshlrev_b64 v[2:3], 2, v[166:167]
	v_lshl_add_u64 v[4:5], s[60:61], 0, v[2:3]
	global_load_dword v6, v[4:5], off
	global_load_dword v7, v[4:5], off offset:2048
	s_mov_b32 s3, 0x3fb8aa3b
	s_mov_b32 s4, 0x42b17218
	v_lshl_add_u64 v[2:3], s[80:81], 0, v[2:3]
	s_waitcnt vmcnt(0)
	v_sub_f32_e32 v4, v7, v6
	v_mul_f32_e32 v5, 0x3fb8aa3b, v4
	v_fma_f32 v6, v4, s3, -v5
	v_rndne_f32_e32 v7, v5
	v_fmamk_f32 v6, v4, 0x32a5705f, v6
	v_sub_f32_e32 v5, v5, v7
	v_add_f32_e32 v5, v5, v6
	v_cvt_i32_f32_e32 v7, v7
	v_exp_f32_e32 v5, v5
	s_mov_b32 s3, 0xc2ce8ed0
	v_cmp_ngt_f32_e32 vcc, s3, v4
	v_mov_b32_e32 v6, 0x7f800000
	v_ldexp_f32 v5, v5, v7
	v_cndmask_b32_e32 v5, 0, v5, vcc
	v_cmp_nlt_f32_e32 vcc, s4, v4
	s_nop 1
	v_cndmask_b32_e32 v4, v6, v5, vcc
	v_add_f32_e32 v4, 1.0, v4
	v_div_scale_f32 v5, s[4:5], v4, v4, 1.0
	v_rcp_f32_e32 v6, v5
	v_div_scale_f32 v7, vcc, 1.0, v4, 1.0
	v_fma_f32 v8, -v5, v6, 1.0
	v_fmac_f32_e32 v6, v8, v6
	v_mul_f32_e32 v8, v7, v6
	v_fma_f32 v9, -v5, v8, v7
	v_fmac_f32_e32 v8, v9, v6
	v_fma_f32 v5, -v5, v8, v7
	v_div_fmas_f32 v5, v5, v6, v8
	v_add_co_u32_e32 v2, vcc, 0x1000, v2
	v_div_fixup_f32 v4, v5, v4, 1.0
	s_nop 0
	v_addc_co_u32_e32 v3, vcc, 0, v3, vcc
	global_store_dword v[2:3], v4, off
